# attention C flash loop: L2 touch-prefetch of the K/V tile two iterations ahead (dummy dword loads issued after the real tile loads; vmcnt staircase shifted)
# baseline (speedup 1.0000x reference)
; template <int DQK, int DV, bool BIAS, int TK> ...
;     ...
;     ATT_LOAD(t0); ATT_STORE(0); __syncthreads();
;     const int koff = l31 * KP + hi * 16;
;     const int voff = (4 * hi + ((lane & 15) >> 2)) * VP + (16 * ((lane >> 4) & 1) + 4 * (lane & 3)) * 2;
;     for (int t = t0; t < t1; ++t) {
;         const int cur = (t - t0) & 1;
;         ATT_LOAD((t + 1 < t1 ? t + 1 : t1 - 1));
;     ...
;         ATT_STORE(cur ^ 1);
.LBB0_2290:
	s_or_b64 exec, exec, s[66:67]
	s_xor_b32 s0, s82, 1
	s_mul_i32 s1, s0, 0x6800
	s_add_i32 s1, s1, 0
	v_add3_u32 v32, s1, v149, v184
	s_waitcnt vmcnt(9)
	ds_write_b128 v32, v[120:123] offset:1024
	v_add3_u32 v32, s1, v185, v186
	s_lshl_b32 s0, s0, 11
	s_waitcnt vmcnt(8)
	ds_write_b128 v32, v[124:127] offset:1024
	v_add3_u32 v32, s1, v187, v188
	s_sub_i32 s0, s1, s0
	s_waitcnt vmcnt(7)
	ds_write_b128 v32, v[128:131] offset:1024
	v_add3_u32 v32, s0, v194, v197
	v_cmp_eq_u32_e32 vcc, s80, v199
	s_waitcnt vmcnt(6)
	ds_write_b128 v32, v[136:139] offset:54272
	v_add3_u32 v32, s0, v195, v198
	s_or_b64 s[62:63], vcc, s[62:63]
	v_mov_b32_e32 v201, v199
	s_mov_b32 s10, s81
	s_waitcnt vmcnt(5)
	ds_write_b128 v32, v[132:135] offset:54272
	s_waitcnt lgkmcnt(0)
	s_barrier
	s_andn2_b64 exec, exec, s[62:63]
	s_cbranch_execz .LBB0_2297
.LBB0_2291:
	s_add_i32 s81, s10, 1
	s_cmp_lt_u32 s81, s79
	s_cselect_b32 s0, s81, s50
	s_ashr_i32 s1, s0, 31
	s_lshl_b64 s[0:1], s[0:1], 7
	v_lshl_add_u64 v[32:33], s[0:1], 0, v[152:153]
	v_lshlrev_b64 v[34:35], 6, v[32:33]
	v_lshl_add_u64 v[34:35], v[170:171], 0, v[34:35]
	v_lshlrev_b64 v[32:33], 8, v[32:33]
	v_lshl_add_u64 v[34:35], v[34:35], 0, s[58:59]
	v_lshl_add_u64 v[32:33], v[162:163], 0, v[32:33]
	v_cndmask_b32_e64 v33, v33, v35, s[2:3]
	v_cndmask_b32_e64 v32, v32, v34, s[2:3]
	global_load_dwordx4 v[120:123], v[32:33], off
	v_lshl_add_u64 v[32:33], s[0:1], 0, v[154:155]
	v_lshlrev_b64 v[34:35], 6, v[32:33]
	v_lshl_add_u64 v[34:35], v[172:173], 0, v[34:35]
	v_lshlrev_b64 v[32:33], 8, v[32:33]
	v_lshl_add_u64 v[34:35], v[34:35], 0, s[58:59]
	v_lshl_add_u64 v[32:33], v[164:165], 0, v[32:33]
	v_cndmask_b32_e64 v33, v33, v35, s[4:5]
	v_cndmask_b32_e64 v32, v32, v34, s[4:5]
	global_load_dwordx4 v[124:127], v[32:33], off
	v_lshl_add_u64 v[32:33], s[0:1], 0, v[156:157]
	v_lshlrev_b64 v[34:35], 6, v[32:33]
	v_lshl_add_u64 v[34:35], v[168:169], 0, v[34:35]
	v_lshlrev_b64 v[32:33], 8, v[32:33]
	v_lshl_add_u64 v[34:35], v[34:35], 0, s[58:59]
	v_lshl_add_u64 v[32:33], v[166:167], 0, v[32:33]
	v_cndmask_b32_e64 v33, v33, v35, s[6:7]
	v_cndmask_b32_e64 v32, v32, v34, s[6:7]
	global_load_dwordx4 v[128:131], v[32:33], off
	v_lshl_add_u64 v[32:33], s[0:1], 0, v[158:159]
	v_lshlrev_b64 v[32:33], 8, v[32:33]
	v_lshl_add_u64 v[34:35], s[0:1], 0, v[160:161]
	v_lshl_add_u64 v[32:33], v[174:175], 0, v[32:33]
	v_lshlrev_b64 v[34:35], 8, v[34:35]
	v_lshl_add_u64 v[34:35], v[176:177], 0, v[34:35]
	global_load_dwordx4 v[136:139], v[32:33], off offset:128
	global_load_dwordx4 v[132:135], v[34:35], off offset:128
	s_add_i32 s0, s10, 2
	s_cmp_lt_u32 s0, s79
	s_cselect_b32 s0, s0, s50
	s_ashr_i32 s1, s0, 31
	s_lshl_b64 s[0:1], s[0:1], 7
	v_lshl_add_u64 v[32:33], s[0:1], 0, v[152:153]
	v_lshlrev_b64 v[34:35], 6, v[32:33]
	v_lshl_add_u64 v[34:35], v[170:171], 0, v[34:35]
	v_lshlrev_b64 v[32:33], 8, v[32:33]
	v_lshl_add_u64 v[34:35], v[34:35], 0, s[58:59]
	v_lshl_add_u64 v[32:33], v[162:163], 0, v[32:33]
	v_cndmask_b32_e64 v33, v33, v35, s[2:3]
	v_cndmask_b32_e64 v32, v32, v34, s[2:3]
	global_load_dword v225, v[32:33], off
	v_lshl_add_u64 v[32:33], s[0:1], 0, v[154:155]
	v_lshlrev_b64 v[34:35], 6, v[32:33]
	v_lshl_add_u64 v[34:35], v[172:173], 0, v[34:35]
	v_lshlrev_b64 v[32:33], 8, v[32:33]
	v_lshl_add_u64 v[34:35], v[34:35], 0, s[58:59]
	v_lshl_add_u64 v[32:33], v[164:165], 0, v[32:33]
	v_cndmask_b32_e64 v33, v33, v35, s[4:5]
	v_cndmask_b32_e64 v32, v32, v34, s[4:5]
	global_load_dword v225, v[32:33], off
	v_lshl_add_u64 v[32:33], s[0:1], 0, v[156:157]
	v_lshlrev_b64 v[34:35], 6, v[32:33]
	v_lshl_add_u64 v[34:35], v[168:169], 0, v[34:35]
	v_lshlrev_b64 v[32:33], 8, v[32:33]
	v_lshl_add_u64 v[34:35], v[34:35], 0, s[58:59]
	v_lshl_add_u64 v[32:33], v[166:167], 0, v[32:33]
	v_cndmask_b32_e64 v33, v33, v35, s[6:7]
	v_cndmask_b32_e64 v32, v32, v34, s[6:7]
	global_load_dword v225, v[32:33], off
	v_lshl_add_u64 v[32:33], s[0:1], 0, v[158:159]
	v_lshlrev_b64 v[32:33], 8, v[32:33]
	v_lshl_add_u64 v[34:35], s[0:1], 0, v[160:161]
	v_lshl_add_u64 v[32:33], v[174:175], 0, v[32:33]
	v_lshlrev_b64 v[34:35], 8, v[34:35]
	v_lshl_add_u64 v[34:35], v[176:177], 0, v[34:35]
	global_load_dword v225, v[32:33], off offset:128
	global_load_dword v225, v[34:35], off offset:128
	v_cmp_ge_u32_e32 vcc, s10, v193
	s_or_b64 s[0:1], s[64:65], vcc
	v_add_u32_e32 v199, 0x80, v201
	s_and_saveexec_b64 s[8:9], s[0:1]
	s_xor_b64 s[0:1], exec, s[8:9]
	v_add_u32_e32 v199, 0x80, v201
	s_or_saveexec_b64 s[66:67], s[0:1]
	s_and_b32 s82, s10, 1
	s_xor_b64 exec, exec, s[66:67]
	s_cbranch_execz .LBB0_2290
; #define LAS __attribute__((address_space(3)))
; template <int DQK, int DV, bool BIAS, int TK> ...
;     ...
;             const LAS unsigned char* kb = kb0 + cur * KBUF + koff; const LAS unsigned char* vb = vb0 + cur * VBUF + voff;
;             f32x16 p[NPB];
;             const int tk0 = t * TK;
;             const bool far = BIAS && (qpos_w0 - (kpos0 + tk0 + TK - 64) >= 192);
;             const float pinit = far ? tab[254] : 0.f;
; #pragma unroll
;             for (int q = 0; q < NPB; ++q)
; #pragma unroll
;                 for (int r = 0; r < 16; ++r) p[q][r] = pinit - m_run;
; #pragma unroll
;             for (int ks = 0; ks < DQK / 16; ++ks)
; #pragma unroll
;                 for (int q = 0; q < NPB; ++q) {
;                     const bf16x8 a = *(const LAS bf16x8*)(kb + q * 32 * KP + ks * 32);
;                     p[q] = __builtin_amdgcn_mfma_f32_32x32x16_bf16(a, qf[ks], p[q], 0, 0, 0);
;                 }
;             __builtin_amdgcn_sched_barrier(0);
;             asm volatile("s_nop 15\n\ts_nop 15" ::: "memory");
;             if (BIAS) {
;                 const int tkpos = kpos0 + tk0;
;                 if (!far) { const int base = qpos - (tkpos + 4 * hi) + 63;
; #pragma unroll
;                     for (int q = 0; q < NPB; ++q)
; #pragma unroll
;                         for (int r = 0; r < 16; ++r) { int i0 = base - ((r & 3) + 8 * (r >> 2)) - 32 * q; i0 = i0 > 254 ? 254 : i0; p[q][r] += tab[i0]; } }
;             }
;             if (tk0 < klo || tk0 + TK > khi) {
;                 asm volatile("" ::: "memory");
; #pragma unroll
;                 for (int q = 0; q < NPB; ++q)
; #pragma unroll
;                     for (int r = 0; r < 16; ++r) { const int key = tk0 + 32 * q + 4 * hi + (r & 3) + 8 * (r >> 2); if (key < klo || key >= khi) p[q][r] = NEGBIG; }
	s_mul_i32 s0, s82, 0x6800
	v_add_u32_e32 v142, s0, v192
	ds_read_b128 v[48:51], v142 offset:1024
	ds_read_b128 v[202:205], v142 offset:1056
	v_sub_f32_e32 v32, 0, v189
	v_mov_b32_e32 v33, v32
	v_mov_b32_e32 v34, v32
	v_mov_b32_e32 v35, v32
	v_mov_b32_e32 v36, v32
	v_mov_b32_e32 v37, v32
	v_mov_b32_e32 v38, v32
	v_mov_b32_e32 v39, v32
	v_mov_b32_e32 v40, v32
	v_mov_b32_e32 v41, v32
	v_mov_b32_e32 v42, v32
	v_mov_b32_e32 v43, v32
	v_mov_b32_e32 v44, v32
	v_mov_b32_e32 v45, v32
	v_mov_b32_e32 v46, v32
	v_mov_b32_e32 v47, v32
	s_waitcnt lgkmcnt(1)
	s_nop 0
	v_mfma_f32_32x32x16_bf16 v[80:95], v[48:51], v[96:99], v[32:47]
	ds_read_b128 v[48:51], v142 offset:7680
	ds_read_b128 v[206:209], v142 offset:7712
	ds_read_b128 v[210:213], v142 offset:14336
	ds_read_b128 v[214:217], v142 offset:14368
	s_waitcnt lgkmcnt(3)
	v_mfma_f32_32x32x16_bf16 v[64:79], v[48:51], v[96:99], v[32:47]
	s_waitcnt lgkmcnt(1)
	v_mfma_f32_32x32x16_bf16 v[48:63], v[210:213], v[96:99], v[32:47]
	ds_read_b128 v[210:213], v142 offset:20992
	ds_read_b128 v[218:221], v142 offset:21024
	v_mfma_f32_32x32x16_bf16 v[80:95], v[202:205], v[100:103], v[80:95]
	s_waitcnt lgkmcnt(1)
	v_mfma_f32_32x32x16_bf16 v[32:47], v[210:213], v[96:99], v[32:47]
	v_mfma_f32_32x32x16_bf16 v[64:79], v[206:209], v[100:103], v[64:79]
	ds_read_b128 v[202:205], v142 offset:1088
	ds_read_b128 v[206:209], v142 offset:1120
	v_mfma_f32_32x32x16_bf16 v[48:63], v[214:217], v[100:103], v[48:63]
	s_waitcnt lgkmcnt(1)
	v_mfma_f32_32x32x16_bf16 v[80:95], v[202:205], v[104:107], v[80:95]
	ds_read_b128 v[202:205], v142 offset:7744
	ds_read_b128 v[210:213], v142 offset:7776
	v_mfma_f32_32x32x16_bf16 v[32:47], v[218:221], v[100:103], v[32:47]
	s_waitcnt lgkmcnt(1)
	v_mfma_f32_32x32x16_bf16 v[64:79], v[202:205], v[104:107], v[64:79]
	ds_read_b128 v[202:205], v142 offset:14400
	ds_read_b128 v[214:217], v142 offset:14432
	s_waitcnt lgkmcnt(1)
	v_mfma_f32_32x32x16_bf16 v[48:63], v[202:205], v[104:107], v[48:63]
	ds_read_b128 v[202:205], v142 offset:21056
	ds_read_b128 v[218:221], v142 offset:21088
	v_mfma_f32_32x32x16_bf16 v[80:95], v[206:209], v[108:111], v[80:95]
	s_waitcnt lgkmcnt(1)
	v_mfma_f32_32x32x16_bf16 v[32:47], v[202:205], v[104:107], v[32:47]
	ds_read_b128 v[202:205], v142 offset:1152
	ds_read_b128 v[206:209], v142 offset:1184
	v_mfma_f32_32x32x16_bf16 v[64:79], v[210:213], v[108:111], v[64:79]
	v_mfma_f32_32x32x16_bf16 v[48:63], v[214:217], v[108:111], v[48:63]
	s_waitcnt lgkmcnt(1)
	v_mfma_f32_32x32x16_bf16 v[80:95], v[202:205], v[112:115], v[80:95]
	ds_read_b128 v[202:205], v142 offset:7808
	ds_read_b128 v[210:213], v142 offset:7840
	v_mfma_f32_32x32x16_bf16 v[32:47], v[218:221], v[108:111], v[32:47]
	s_waitcnt lgkmcnt(1)
	v_mfma_f32_32x32x16_bf16 v[64:79], v[202:205], v[112:115], v[64:79]
	ds_read_b128 v[202:205], v142 offset:14464
	ds_read_b128 v[214:217], v142 offset:14496
	s_waitcnt lgkmcnt(1)
	v_mfma_f32_32x32x16_bf16 v[48:63], v[202:205], v[112:115], v[48:63]
	ds_read_b128 v[202:205], v142 offset:21120
	ds_read_b128 v[218:221], v142 offset:21152
	s_waitcnt lgkmcnt(1)
	v_mfma_f32_32x32x16_bf16 v[32:47], v[202:205], v[112:115], v[32:47]
	v_mfma_f32_32x32x16_bf16 v[80:95], v[206:209], v[116:119], v[80:95]
	v_mfma_f32_32x32x16_bf16 v[64:79], v[210:213], v[116:119], v[64:79]
	v_mfma_f32_32x32x16_bf16 v[48:63], v[214:217], v[116:119], v[48:63]
	s_waitcnt lgkmcnt(0)
	v_mfma_f32_32x32x16_bf16 v[32:47], v[218:221], v[116:119], v[32:47]
	s_nop 15
	s_nop 15
	v_cmp_gt_i32_e32 vcc, v199, v190
	s_and_saveexec_b64 s[68:69], vcc
	s_cbranch_execz .LBB0_2287
	v_add_u32_e32 v142, v191, v201
	v_add_u32_e32 v178, 1, v142
	v_cmp_lt_i32_e64 s[0:1], v178, v190
	v_add_u32_e32 v178, 2, v142
	v_cmp_lt_i32_e64 s[8:9], v178, v190
	v_add_u32_e32 v178, 3, v142
	v_cmp_lt_i32_e64 s[10:11], v178, v190
	v_add_u32_e32 v178, 8, v142
	v_cmp_lt_i32_e64 s[12:13], v178, v190
	v_add_u32_e32 v178, 9, v142
	v_cmp_lt_i32_e64 s[14:15], v178, v190
	v_add_u32_e32 v178, 10, v142
	v_cmp_lt_i32_e64 s[20:21], v178, v190
	v_add_u32_e32 v178, 11, v142
	v_cmp_lt_i32_e64 s[22:23], v178, v190
	v_add_u32_e32 v178, 16, v142
	v_cmp_lt_i32_e64 s[24:25], v178, v190
	v_add_u32_e32 v178, 17, v142
	v_cmp_lt_i32_e64 s[26:27], v178, v190
	v_add_u32_e32 v178, 18, v142
	v_cmp_lt_i32_e64 s[28:29], v178, v190
	v_add_u32_e32 v178, 19, v142
	v_cmp_lt_i32_e64 s[30:31], v178, v190
	v_add_u32_e32 v178, 24, v142
	v_cmp_lt_i32_e64 s[34:35], v178, v190
	v_add_u32_e32 v178, 25, v142
	v_cmp_lt_i32_e64 s[36:37], v178, v190
	v_add_u32_e32 v178, 26, v142
	v_cmp_lt_i32_e64 s[38:39], v178, v190
	v_add_u32_e32 v178, 27, v142
	v_cmp_lt_i32_e64 s[40:41], v178, v190
	s_or_b64 s[38:39], s[40:41], s[38:39]
	s_or_b64 s[36:37], s[38:39], s[36:37]
	s_or_b64 s[34:35], s[36:37], s[34:35]
	s_or_b64 s[30:31], s[34:35], s[30:31]
	s_or_b64 s[28:29], s[30:31], s[28:29]
	s_or_b64 s[26:27], s[28:29], s[26:27]
	s_or_b64 s[24:25], s[26:27], s[24:25]
	s_or_b64 s[22:23], s[24:25], s[22:23]
	s_or_b64 s[20:21], s[22:23], s[20:21]
	s_or_b64 s[14:15], s[20:21], s[14:15]
	s_or_b64 s[12:13], s[14:15], s[12:13]
	s_or_b64 s[10:11], s[12:13], s[10:11]
	s_or_b64 s[8:9], s[10:11], s[8:9]
	v_cmp_lt_i32_e32 vcc, v142, v190
	s_or_b64 s[0:1], s[8:9], s[0:1]
	s_or_b64 vcc, s[0:1], vcc
	v_add_u32_e32 v178, 32, v142
	v_cndmask_b32_e32 v80, v182, v80, vcc
	v_cmp_lt_i32_e32 vcc, v178, v190
	v_add_u32_e32 v178, 33, v142
	v_cndmask_b32_e64 v81, v182, v81, s[0:1]
	v_cmp_lt_i32_e64 s[0:1], v178, v190
	v_add_u32_e32 v178, 34, v142
	v_cndmask_b32_e64 v82, v182, v82, s[8:9]
	v_cmp_lt_i32_e64 s[8:9], v178, v190
	v_add_u32_e32 v178, 35, v142
	v_cndmask_b32_e64 v83, v182, v83, s[10:11]
	v_cmp_lt_i32_e64 s[10:11], v178, v190
; template <int DQK, int DV, bool BIAS, int TK> ...
;     ...
;             if (tk0 < klo || tk0 + TK > khi) {
;                 asm volatile("" ::: "memory");
; #pragma unroll
;                 for (int q = 0; q < NPB; ++q)
; #pragma unroll
;                     for (int r = 0; r < 16; ++r) { const int key = tk0 + 32 * q + 4 * hi + (r & 3) + 8 * (r >> 2); if (key < klo || key >= khi) p[q][r] = NEGBIG; }
;             }
	v_add_u32_e32 v178, 40, v142
	v_cndmask_b32_e64 v84, v182, v84, s[12:13]
	v_cmp_lt_i32_e64 s[12:13], v178, v190
	v_add_u32_e32 v178, 41, v142
	v_cndmask_b32_e64 v85, v182, v85, s[14:15]
	v_cmp_lt_i32_e64 s[14:15], v178, v190
	v_add_u32_e32 v178, 42, v142
	v_cndmask_b32_e64 v86, v182, v86, s[20:21]
	v_cmp_lt_i32_e64 s[20:21], v178, v190
	v_add_u32_e32 v178, 43, v142
	v_cndmask_b32_e64 v87, v182, v87, s[22:23]
	v_cmp_lt_i32_e64 s[22:23], v178, v190
	v_add_u32_e32 v178, 48, v142
	v_cndmask_b32_e64 v88, v182, v88, s[24:25]
	v_cmp_lt_i32_e64 s[24:25], v178, v190
	v_add_u32_e32 v178, 49, v142
	v_cndmask_b32_e64 v89, v182, v89, s[26:27]
	v_cmp_lt_i32_e64 s[26:27], v178, v190
	v_add_u32_e32 v178, 50, v142
	v_cndmask_b32_e64 v90, v182, v90, s[28:29]
	v_cmp_lt_i32_e64 s[28:29], v178, v190
	v_add_u32_e32 v178, 51, v142
	v_cndmask_b32_e64 v91, v182, v91, s[30:31]
	v_cmp_lt_i32_e64 s[30:31], v178, v190
	v_add_u32_e32 v178, 56, v142
	v_cndmask_b32_e64 v92, v182, v92, s[34:35]
	v_cmp_lt_i32_e64 s[34:35], v178, v190
	v_add_u32_e32 v178, 57, v142
	v_cndmask_b32_e64 v93, v182, v93, s[36:37]
	v_cmp_lt_i32_e64 s[36:37], v178, v190
	v_add_u32_e32 v178, 58, v142
	v_cndmask_b32_e64 v94, v182, v94, s[38:39]
	v_cmp_lt_i32_e64 s[38:39], v178, v190
	v_add_u32_e32 v178, 59, v142
	v_cndmask_b32_e64 v95, v182, v95, s[40:41]
	v_cmp_lt_i32_e64 s[40:41], v178, v190
	s_or_b64 s[38:39], s[40:41], s[38:39]
	s_or_b64 s[36:37], s[38:39], s[36:37]
	s_or_b64 s[34:35], s[36:37], s[34:35]
	s_or_b64 s[30:31], s[34:35], s[30:31]
	s_or_b64 s[28:29], s[30:31], s[28:29]
	s_or_b64 s[26:27], s[28:29], s[26:27]
	s_or_b64 s[24:25], s[26:27], s[24:25]
	s_or_b64 s[22:23], s[24:25], s[22:23]
	s_or_b64 s[20:21], s[22:23], s[20:21]
	s_or_b64 s[14:15], s[20:21], s[14:15]
	s_or_b64 s[12:13], s[14:15], s[12:13]
	s_or_b64 s[10:11], s[12:13], s[10:11]
	s_or_b64 s[8:9], s[10:11], s[8:9]
	s_or_b64 s[0:1], s[8:9], s[0:1]
	s_or_b64 vcc, s[0:1], vcc
	v_add_u32_e32 v178, 64, v142
	v_cndmask_b32_e32 v64, v182, v64, vcc
	v_cmp_lt_i32_e32 vcc, v178, v190
	v_add_u32_e32 v178, 0x41, v142
	v_cndmask_b32_e64 v65, v182, v65, s[0:1]
	v_cmp_lt_i32_e64 s[0:1], v178, v190
	v_add_u32_e32 v178, 0x42, v142
	v_cndmask_b32_e64 v66, v182, v66, s[8:9]
	v_cmp_lt_i32_e64 s[8:9], v178, v190
	v_add_u32_e32 v178, 0x43, v142
	v_cndmask_b32_e64 v67, v182, v67, s[10:11]
	v_cmp_lt_i32_e64 s[10:11], v178, v190
	v_add_u32_e32 v178, 0x48, v142
	v_cndmask_b32_e64 v68, v182, v68, s[12:13]
	v_cmp_lt_i32_e64 s[12:13], v178, v190
	v_add_u32_e32 v178, 0x49, v142
	v_cndmask_b32_e64 v69, v182, v69, s[14:15]
	v_cmp_lt_i32_e64 s[14:15], v178, v190
	v_add_u32_e32 v178, 0x4a, v142
	v_cndmask_b32_e64 v70, v182, v70, s[20:21]
	v_cmp_lt_i32_e64 s[20:21], v178, v190
	v_add_u32_e32 v178, 0x4b, v142
	v_cndmask_b32_e64 v71, v182, v71, s[22:23]
	v_cmp_lt_i32_e64 s[22:23], v178, v190
	v_add_u32_e32 v178, 0x50, v142
	v_cndmask_b32_e64 v72, v182, v72, s[24:25]
	v_cmp_lt_i32_e64 s[24:25], v178, v190
	v_add_u32_e32 v178, 0x51, v142
	v_cndmask_b32_e64 v73, v182, v73, s[26:27]
	v_cmp_lt_i32_e64 s[26:27], v178, v190
	v_add_u32_e32 v178, 0x52, v142
	v_cndmask_b32_e64 v74, v182, v74, s[28:29]
	v_cmp_lt_i32_e64 s[28:29], v178, v190
	v_add_u32_e32 v178, 0x53, v142
	v_cndmask_b32_e64 v75, v182, v75, s[30:31]
	v_cmp_lt_i32_e64 s[30:31], v178, v190
	v_add_u32_e32 v178, 0x58, v142
	v_cndmask_b32_e64 v76, v182, v76, s[34:35]
	v_cmp_lt_i32_e64 s[34:35], v178, v190
	v_add_u32_e32 v178, 0x59, v142
	v_cndmask_b32_e64 v77, v182, v77, s[36:37]
	v_cmp_lt_i32_e64 s[36:37], v178, v190
	v_add_u32_e32 v178, 0x5a, v142
	v_cndmask_b32_e64 v78, v182, v78, s[38:39]
	v_cmp_lt_i32_e64 s[38:39], v178, v190
	v_add_u32_e32 v178, 0x5b, v142
	v_cndmask_b32_e64 v79, v182, v79, s[40:41]
; template <int DQK, int DV, bool BIAS, int TK> ...
;     ...
;             if (tk0 < klo || tk0 + TK > khi) {
;                 asm volatile("" ::: "memory");
; #pragma unroll
;                 for (int q = 0; q < NPB; ++q)
; #pragma unroll
;                     for (int r = 0; r < 16; ++r) { const int key = tk0 + 32 * q + 4 * hi + (r & 3) + 8 * (r >> 2); if (key < klo || key >= khi) p[q][r] = NEGBIG; }
;             }
	v_cmp_lt_i32_e64 s[40:41], v178, v190
	s_or_b64 s[38:39], s[40:41], s[38:39]
	s_or_b64 s[36:37], s[38:39], s[36:37]
	s_or_b64 s[34:35], s[36:37], s[34:35]
	s_or_b64 s[30:31], s[34:35], s[30:31]
	s_or_b64 s[28:29], s[30:31], s[28:29]
	s_or_b64 s[26:27], s[28:29], s[26:27]
	s_or_b64 s[24:25], s[26:27], s[24:25]
	s_or_b64 s[22:23], s[24:25], s[22:23]
	s_or_b64 s[20:21], s[22:23], s[20:21]
	s_or_b64 s[14:15], s[20:21], s[14:15]
	s_or_b64 s[12:13], s[14:15], s[12:13]
	s_or_b64 s[10:11], s[12:13], s[10:11]
	s_or_b64 s[8:9], s[10:11], s[8:9]
	s_or_b64 s[0:1], s[8:9], s[0:1]
	s_or_b64 vcc, s[0:1], vcc
	v_add_u32_e32 v178, 0x60, v142
	v_cndmask_b32_e32 v48, v182, v48, vcc
	v_cmp_lt_i32_e32 vcc, v178, v190
	v_add_u32_e32 v178, 0x61, v142
	v_cndmask_b32_e64 v49, v182, v49, s[0:1]
	v_cmp_lt_i32_e64 s[0:1], v178, v190
	v_add_u32_e32 v178, 0x62, v142
	v_cndmask_b32_e64 v50, v182, v50, s[8:9]
	v_cmp_lt_i32_e64 s[8:9], v178, v190
	v_add_u32_e32 v178, 0x63, v142
	v_cndmask_b32_e64 v51, v182, v51, s[10:11]
	v_cmp_lt_i32_e64 s[10:11], v178, v190
	v_add_u32_e32 v178, 0x68, v142
	v_cndmask_b32_e64 v52, v182, v52, s[12:13]
	v_cmp_lt_i32_e64 s[12:13], v178, v190
	v_add_u32_e32 v178, 0x69, v142
	v_cndmask_b32_e64 v53, v182, v53, s[14:15]
	v_cmp_lt_i32_e64 s[14:15], v178, v190
	v_add_u32_e32 v178, 0x6a, v142
	v_cndmask_b32_e64 v54, v182, v54, s[20:21]
	v_cmp_lt_i32_e64 s[20:21], v178, v190
	v_add_u32_e32 v178, 0x6b, v142
	v_cndmask_b32_e64 v55, v182, v55, s[22:23]
	v_cmp_lt_i32_e64 s[22:23], v178, v190
	v_add_u32_e32 v178, 0x70, v142
	v_cndmask_b32_e64 v56, v182, v56, s[24:25]
	v_cmp_lt_i32_e64 s[24:25], v178, v190
	v_add_u32_e32 v178, 0x71, v142
	v_cndmask_b32_e64 v57, v182, v57, s[26:27]
	v_cmp_lt_i32_e64 s[26:27], v178, v190
	v_add_u32_e32 v178, 0x72, v142
	v_cndmask_b32_e64 v58, v182, v58, s[28:29]
	v_cmp_lt_i32_e64 s[28:29], v178, v190
	v_add_u32_e32 v178, 0x73, v142
	v_cndmask_b32_e64 v59, v182, v59, s[30:31]
	v_cmp_lt_i32_e64 s[30:31], v178, v190
	v_add_u32_e32 v178, 0x78, v142
	v_cndmask_b32_e64 v60, v182, v60, s[34:35]
	v_cmp_lt_i32_e64 s[34:35], v178, v190
	v_add_u32_e32 v178, 0x79, v142
	v_cndmask_b32_e64 v61, v182, v61, s[36:37]
	v_cmp_lt_i32_e64 s[36:37], v178, v190
	v_add_u32_e32 v178, 0x7a, v142
	v_add_u32_e32 v142, 0x7b, v142
	v_cndmask_b32_e64 v63, v182, v63, s[40:41]
	v_cndmask_b32_e64 v62, v182, v62, s[38:39]
	v_cmp_lt_i32_e64 s[38:39], v178, v190
	v_cmp_lt_i32_e64 s[40:41], v142, v190
	s_or_b64 s[38:39], s[40:41], s[38:39]
	s_or_b64 s[36:37], s[38:39], s[36:37]
	s_or_b64 s[34:35], s[36:37], s[34:35]
	s_or_b64 s[30:31], s[34:35], s[30:31]
	s_or_b64 s[28:29], s[30:31], s[28:29]
	s_or_b64 s[26:27], s[28:29], s[26:27]
	s_or_b64 s[24:25], s[26:27], s[24:25]
	s_or_b64 s[22:23], s[24:25], s[22:23]
	s_or_b64 s[20:21], s[22:23], s[20:21]
	s_or_b64 s[14:15], s[20:21], s[14:15]
	s_or_b64 s[12:13], s[14:15], s[12:13]
	s_or_b64 s[10:11], s[12:13], s[10:11]
	s_or_b64 s[8:9], s[10:11], s[8:9]
	s_or_b64 s[0:1], s[8:9], s[0:1]
	s_or_b64 vcc, s[0:1], vcc
	v_cndmask_b32_e64 v47, v182, v47, s[40:41]
	v_cndmask_b32_e64 v46, v182, v46, s[38:39]
	v_cndmask_b32_e64 v45, v182, v45, s[36:37]
	v_cndmask_b32_e64 v44, v182, v44, s[34:35]
	v_cndmask_b32_e64 v43, v182, v43, s[30:31]
	v_cndmask_b32_e64 v42, v182, v42, s[28:29]
	v_cndmask_b32_e64 v41, v182, v41, s[26:27]
	v_cndmask_b32_e64 v40, v182, v40, s[24:25]
	v_cndmask_b32_e64 v39, v182, v39, s[22:23]
	v_cndmask_b32_e64 v38, v182, v38, s[20:21]
	v_cndmask_b32_e64 v37, v182, v37, s[14:15]
	v_cndmask_b32_e64 v36, v182, v36, s[12:13]
	v_cndmask_b32_e64 v35, v182, v35, s[10:11]
	v_cndmask_b32_e64 v34, v182, v34, s[8:9]
	v_cndmask_b32_e64 v33, v182, v33, s[0:1]
	v_cndmask_b32_e32 v32, v182, v32, vcc
	s_branch .LBB0_2287
